# mix_pre low-rank weight loops: next iteration's loads issued one iteration ahead
# baseline (speedup 1.0000x reference)
.LBB0_1057:
	s_or_b64 exec, exec, s[12:13]
	s_waitcnt lgkmcnt(0)
	s_barrier
	global_load_dword v68, v[4:5], off
	global_load_dword v66, v[6:7], off
	s_mov_b32 s12, 0
	v_mov_b64_e32 v[74:75], v[22:23]
	s_waitcnt vmcnt(0)
	v_mov_b32_e32 v69, v68
	v_mov_b32_e32 v72, v68
	v_mov_b32_e32 v73, v68
	v_mov_b32_e32 v67, v66
	v_mov_b32_e32 v70, v66
	v_mov_b32_e32 v71, v66
	v_add_co_u32_e32 v190, vcc, 0x40000, v74
	global_load_dwordx4 v[182:185], v[74:75], off
	s_nop 0
	v_addc_co_u32_e32 v191, vcc, 0, v75, vcc
	global_load_dwordx4 v[186:189], v[190:191], off
.LBB0_1058:
	s_waitcnt vmcnt(0)
	v_mov_b32_e32 v0, v182
	v_mov_b32_e32 v1, v183
	v_mov_b32_e32 v2, v184
	v_mov_b32_e32 v3, v185
	v_mov_b32_e32 v98, v186
	v_mov_b32_e32 v99, v187
	v_mov_b32_e32 v100, v188
	v_mov_b32_e32 v101, v189
	v_add_co_u32_e32 v76, vcc, 0x40000, v74
	s_add_i32 s13, s12, 0
	s_nop 0
	v_addc_co_u32_e32 v77, vcc, 0, v75, vcc
	global_load_dwordx4 v[182:185], v[74:75], off offset:16
	global_load_dwordx4 v[186:189], v[76:77], off offset:16
	v_mov_b32_e32 v96, s13
	ds_read_b128 v[102:105], v96 offset:30720
	ds_read_b128 v[108:111], v96 offset:30736
	ds_read_b128 v[112:115], v96 offset:30976
	ds_read_b128 v[116:119], v96 offset:30992
	ds_read_b128 v[120:123], v96 offset:31744
	ds_read_b128 v[124:127], v96 offset:31760
	ds_read_b128 v[128:131], v96 offset:32000
	ds_read_b128 v[132:135], v96 offset:32016
	ds_read_b128 v[138:141], v96 offset:28672
	ds_read_b128 v[142:145], v96 offset:28688
	ds_read_b128 v[146:149], v96 offset:29696
	ds_read_b128 v[150:153], v96 offset:29712
	ds_read_b128 v[154:157], v96 offset:28928
	ds_read_b128 v[158:161], v96 offset:28944
	ds_read_b128 v[162:165], v96 offset:29952
	ds_read_b128 v[166:169], v96 offset:29968
	s_waitcnt lgkmcnt(7)
	v_mov_b32_e32 v76, v138
	s_waitcnt lgkmcnt(5)
	v_mov_b32_e32 v77, v146
	v_mov_b32_e32 v146, v139
	v_mov_b32_e32 v138, v140
	v_mov_b32_e32 v139, v148
	v_mov_b32_e32 v148, v141
	v_mov_b32_e32 v140, v142
	s_waitcnt lgkmcnt(4)
	v_mov_b32_e32 v141, v150
	v_mov_b32_e32 v150, v143
	v_mov_b32_e32 v142, v144
	v_mov_b32_e32 v143, v152
	v_mov_b32_e32 v152, v145
	s_waitcnt lgkmcnt(3)
	v_mov_b32_e32 v144, v154
	s_waitcnt lgkmcnt(1)
	v_mov_b32_e32 v145, v162
	v_mov_b32_e32 v162, v155
	v_mov_b32_e32 v154, v156
	v_mov_b32_e32 v155, v164
	v_mov_b32_e32 v164, v157
	v_mov_b32_e32 v156, v158
	s_waitcnt lgkmcnt(0)
	v_mov_b32_e32 v157, v166
	v_mov_b32_e32 v166, v159
	v_mov_b32_e32 v158, v160
	v_mov_b32_e32 v159, v168
	v_mov_b32_e32 v168, v161
	s_add_i32 s12, s12, 32
	s_cmpk_lg_i32 s12, 0x100
	v_lshl_add_u64 v[74:75], v[74:75], 0, 16
	v_lshlrev_b32_e32 v160, 16, v0
	v_and_b32_e32 v161, 0xffff0000, v0
	v_lshlrev_b32_e32 v170, 16, v2
	v_and_b32_e32 v171, 0xffff0000, v2
	v_pk_mul_f32 v[120:121], v[120:121], v[160:161]
	v_pk_fma_f32 v[68:69], v[76:77], v[160:161], v[68:69] op_sel_hi:[1,0,1]
	v_lshlrev_b32_e32 v0, 16, v1
	v_and_b32_e32 v1, 0xffff0000, v1
	v_mul_f32_e32 v102, v102, v160
	v_mul_f32_e32 v172, v103, v161
	v_pk_mul_f32 v[124:125], v[124:125], v[170:171]
	v_pk_fma_f32 v[68:69], v[146:147], v[160:161], v[68:69] op_sel:[0,1,0]
	v_mov_b32_e32 v103, v120
	v_mov_b32_e32 v173, v121
	v_lshlrev_b32_e32 v120, 16, v98
	v_and_b32_e32 v121, 0xffff0000, v98
	v_pk_mul_f32 v[122:123], v[122:123], v[0:1]
	v_mul_f32_e32 v176, v109, v171
	v_mov_b32_e32 v109, v124
	v_mov_b32_e32 v177, v125
	v_pk_fma_f32 v[68:69], v[138:139], v[0:1], v[68:69] op_sel_hi:[1,0,1]
	v_pk_add_f32 v[72:73], v[72:73], v[102:103]
	v_pk_mul_f32 v[124:125], v[128:129], v[120:121]
	v_pk_fma_f32 v[66:67], v[144:145], v[120:121], v[66:67] op_sel_hi:[1,0,1]
	v_lshlrev_b32_e32 v2, 16, v3
	v_and_b32_e32 v3, 0xffff0000, v3
	v_mul_f32_e32 v104, v104, v0
	v_mul_f32_e32 v174, v105, v1
	v_mov_b32_e32 v105, v122
	v_lshlrev_b32_e32 v98, 16, v99
	v_and_b32_e32 v99, 0xffff0000, v99
	v_mul_f32_e32 v102, v112, v120
	v_pk_fma_f32 v[0:1], v[148:149], v[0:1], v[68:69] op_sel:[0,1,0]
	v_pk_add_f32 v[68:69], v[72:73], v[172:173]
	v_pk_fma_f32 v[66:67], v[162:163], v[120:121], v[66:67] op_sel:[0,1,0]
	v_mov_b32_e32 v103, v124
	v_pk_mul_f32 v[126:127], v[126:127], v[2:3]
	v_mov_b32_e32 v175, v123
	v_mul_f32_e32 v112, v113, v121
	v_pk_mul_f32 v[128:129], v[130:131], v[98:99]
	v_mov_b32_e32 v113, v125
	v_pk_fma_f32 v[0:1], v[140:141], v[170:171], v[0:1] op_sel_hi:[1,0,1]
	v_pk_add_f32 v[68:69], v[68:69], v[104:105]
	v_pk_fma_f32 v[66:67], v[154:155], v[98:99], v[66:67] op_sel_hi:[1,0,1]
	v_pk_add_f32 v[70:71], v[70:71], v[102:103]
	v_mul_f32_e32 v108, v108, v170
	v_mov_b32_e32 v77, v126
	v_lshlrev_b32_e32 v122, 16, v100
	v_and_b32_e32 v123, 0xffff0000, v100
	v_mul_f32_e32 v114, v114, v98
	v_mul_f32_e32 v126, v115, v99
	v_mov_b32_e32 v115, v128
	v_pk_fma_f32 v[0:1], v[150:151], v[170:171], v[0:1] op_sel:[0,1,0]
	v_pk_add_f32 v[68:69], v[68:69], v[174:175]
	v_pk_fma_f32 v[66:67], v[164:165], v[98:99], v[66:67] op_sel:[0,1,0]
	v_pk_add_f32 v[70:71], v[70:71], v[112:113]
	v_mul_f32_e32 v76, v110, v2
	v_mul_f32_e32 v110, v111, v3
	v_mov_b32_e32 v111, v127
	v_pk_mul_f32 v[132:133], v[132:133], v[122:123]
	v_mov_b32_e32 v127, v129
	v_pk_fma_f32 v[0:1], v[142:143], v[2:3], v[0:1] op_sel_hi:[1,0,1]
	v_pk_add_f32 v[72:73], v[68:69], v[108:109]
	v_pk_fma_f32 v[66:67], v[156:157], v[122:123], v[66:67] op_sel_hi:[1,0,1]
	v_pk_add_f32 v[70:71], v[70:71], v[114:115]
	v_lshlrev_b32_e32 v100, 16, v101
	v_and_b32_e32 v101, 0xffff0000, v101
	v_mul_f32_e32 v116, v116, v122
	v_mul_f32_e32 v130, v117, v123
	v_mov_b32_e32 v117, v132
	v_pk_fma_f32 v[68:69], v[152:153], v[2:3], v[0:1] op_sel:[0,1,0]
	v_pk_add_f32 v[0:1], v[72:73], v[176:177]
	v_pk_fma_f32 v[2:3], v[166:167], v[122:123], v[66:67] op_sel:[0,1,0]
	v_pk_add_f32 v[66:67], v[70:71], v[126:127]
	v_pk_mul_f32 v[134:135], v[134:135], v[100:101]
	v_mov_b32_e32 v131, v133
	v_pk_add_f32 v[0:1], v[0:1], v[76:77]
	v_pk_add_f32 v[70:71], v[66:67], v[116:117]
	v_mul_f32_e32 v118, v118, v100
	v_mul_f32_e32 v138, v119, v101
	v_mov_b32_e32 v119, v134
	v_pk_add_f32 v[72:73], v[0:1], v[110:111]
	v_pk_add_f32 v[0:1], v[70:71], v[130:131]
	v_mov_b32_e32 v139, v135
	v_pk_fma_f32 v[2:3], v[158:159], v[100:101], v[2:3] op_sel_hi:[1,0,1]
	v_pk_add_f32 v[0:1], v[0:1], v[118:119]
	v_pk_fma_f32 v[66:67], v[168:169], v[100:101], v[2:3] op_sel:[0,1,0]
	v_pk_add_f32 v[70:71], v[0:1], v[138:139]
	s_cbranch_scc1 .LBB0_1058
	v_mov_b32_e32 v2, 0
	s_mov_b32 s12, 0
	v_mov_b64_e32 v[74:75], v[54:55]
	v_mov_b32_e32 v3, v2
	v_mov_b32_e32 v0, v2
	v_mov_b32_e32 v1, v2
	global_load_dwordx4 v[190:193], v[74:75], off
.LBB0_1060:
	s_add_i32 s13, s12, 0
	v_mov_b32_e32 v113, s13
	s_add_i32 s12, s12, 32
	v_lshl_add_u64 v[74:75], v[74:75], 0, 16
	s_cmpk_eq_i32 s12, 0x200
	s_waitcnt vmcnt(0)
	v_mov_b32_e32 v98, v190
	v_mov_b32_e32 v99, v191
	v_mov_b32_e32 v100, v192
	v_mov_b32_e32 v101, v193
	global_load_dwordx4 v[190:193], v[74:75], off
	v_lshlrev_b32_e32 v76, 16, v98
	v_and_b32_e32 v96, 0xffff0000, v98
	v_lshlrev_b32_e32 v112, 16, v99
	v_and_b32_e32 v114, 0xffff0000, v99
	v_lshlrev_b32_e32 v116, 16, v100
	v_and_b32_e32 v118, 0xffff0000, v100
	v_lshlrev_b32_e32 v120, 16, v101
	v_and_b32_e32 v122, 0xffff0000, v101
	ds_read_b128 v[98:101], v113 offset:29184
	ds_read_b128 v[102:105], v113 offset:29200
	ds_read_b128 v[108:111], v113 offset:30208
	s_waitcnt lgkmcnt(2)
	v_mov_b32_e32 v124, v98
	v_mov_b32_e32 v98, v100
	s_waitcnt lgkmcnt(0)
	v_mov_b32_e32 v125, v108
	v_pk_fma_f32 v[2:3], v[124:125], v[76:77], v[2:3] op_sel_hi:[1,0,1]
	v_mov_b32_e32 v108, v99
	v_pk_fma_f32 v[2:3], v[108:109], v[96:97], v[2:3] op_sel_hi:[1,0,1]
	v_mov_b32_e32 v99, v110
	v_pk_fma_f32 v[2:3], v[98:99], v[112:113], v[2:3] op_sel_hi:[1,0,1]
	v_mov_b32_e32 v110, v101
	ds_read_b128 v[98:101], v113 offset:30224
	v_pk_fma_f32 v[2:3], v[110:111], v[114:115], v[2:3] op_sel_hi:[1,0,1]
	v_mov_b32_e32 v108, v102
	s_waitcnt lgkmcnt(0)
	v_mov_b32_e32 v109, v98
	v_pk_fma_f32 v[2:3], v[108:109], v[116:117], v[2:3] op_sel_hi:[1,0,1]
	v_mov_b32_e32 v98, v103
	v_pk_fma_f32 v[2:3], v[98:99], v[118:119], v[2:3] op_sel_hi:[1,0,1]
	v_mov_b32_e32 v98, v104
	v_mov_b32_e32 v99, v100
	v_pk_fma_f32 v[2:3], v[98:99], v[120:121], v[2:3] op_sel_hi:[1,0,1]
	v_mov_b32_e32 v100, v105
	v_pk_fma_f32 v[2:3], v[100:101], v[122:123], v[2:3] op_sel_hi:[1,0,1]
	ds_read_b128 v[98:101], v113 offset:31232
	ds_read_b128 v[102:105], v113 offset:31248
	ds_read_b128 v[108:111], v113 offset:32256
	s_waitcnt lgkmcnt(2)
	v_mov_b32_e32 v124, v98
	s_waitcnt lgkmcnt(0)
	v_mov_b32_e32 v125, v108
	v_pk_fma_f32 v[0:1], v[124:125], v[76:77], v[0:1] op_sel_hi:[1,0,1]
	v_mov_b32_e32 v108, v99
	v_mov_b32_e32 v76, v100
	v_mov_b32_e32 v77, v110
	v_mov_b32_e32 v110, v101
	ds_read_b128 v[98:101], v113 offset:32272
	v_pk_fma_f32 v[0:1], v[108:109], v[96:97], v[0:1] op_sel_hi:[1,0,1]
	s_nop 0
	v_pk_fma_f32 v[0:1], v[76:77], v[112:113], v[0:1] op_sel_hi:[1,0,1]
	v_mov_b32_e32 v76, v102
	v_pk_fma_f32 v[0:1], v[110:111], v[114:115], v[0:1] op_sel_hi:[1,0,1]
	s_waitcnt lgkmcnt(0)
	v_mov_b32_e32 v77, v98
	v_pk_fma_f32 v[0:1], v[76:77], v[116:117], v[0:1] op_sel_hi:[1,0,1]
	v_mov_b32_e32 v98, v103
	v_pk_fma_f32 v[0:1], v[98:99], v[118:119], v[0:1] op_sel_hi:[1,0,1]
	v_mov_b32_e32 v76, v104
	v_mov_b32_e32 v77, v100
	v_pk_fma_f32 v[0:1], v[76:77], v[120:121], v[0:1] op_sel_hi:[1,0,1]
	v_mov_b32_e32 v100, v105
	v_pk_fma_f32 v[0:1], v[100:101], v[122:123], v[0:1] op_sel_hi:[1,0,1]
	s_cbranch_scc0 .LBB0_1060
	global_load_dword v77, v[8:9], off
	global_load_dword v76, v[10:11], off
	v_mul_f32_e32 v74, 0xbfb8aa3b, v68
	v_rndne_f32_e32 v75, v74
	v_sub_f32_e32 v96, v74, v75
	v_fma_f32 v74, v68, s33, -v74
	v_fmac_f32_e32 v74, 0xb2a5705f, v68
	v_add_f32_e32 v74, v96, v74
	v_exp_f32_e32 v74, v74
	v_cvt_i32_f32_e32 v75, v75
	v_cmp_nlt_f32_e32 vcc, s72, v68
	s_lshl_b32 s12, s64, 2
	s_add_i32 s58, s12, 0x2040
	v_ldexp_f32 v74, v74, v75
	v_cndmask_b32_e32 v74, 0, v74, vcc
	v_cmp_ngt_f32_e32 vcc, s79, v68
	s_ashr_i32 s59, s58, 31
	s_nop 0
	v_cndmask_b32_e32 v68, v220, v74, vcc
	v_add_f32_e32 v68, 1.0, v68
	v_div_scale_f32 v74, s[12:13], v68, v68, 1.0
	v_rcp_f32_e32 v75, v74
	s_nop 0
	v_fma_f32 v96, -v74, v75, 1.0
	v_fmac_f32_e32 v75, v96, v75
	v_div_scale_f32 v96, vcc, 1.0, v68, 1.0
	v_mul_f32_e32 v98, v96, v75
	v_fma_f32 v99, -v74, v98, v96
	v_fmac_f32_e32 v98, v99, v75
	v_fma_f32 v74, -v74, v98, v96
	v_div_fmas_f32 v74, v74, v75, v98
	v_div_fixup_f32 v68, v74, v68, 1.0
	v_mul_f32_e32 v68, 0xbf1b459e, v68
	v_mul_f32_e32 v74, 0x3fb8aa3b, v68
	v_fma_f32 v75, v68, s65, -v74
	v_rndne_f32_e32 v96, v74
	v_fmac_f32_e32 v75, 0x32a5705f, v68
	v_sub_f32_e32 v74, v74, v96
	v_add_f32_e32 v74, v74, v75
	v_exp_f32_e32 v74, v74
	v_cvt_i32_f32_e32 v75, v96
	v_cmp_ngt_f32_e32 vcc, s47, v68
	v_ldexp_f32 v74, v74, v75
	s_nop 0
	v_cndmask_b32_e32 v74, 0, v74, vcc
	v_cmp_nlt_f32_e32 vcc, s37, v68
	s_nop 1
	v_cndmask_b32_e32 v68, v220, v74, vcc
	v_mul_f32_e32 v74, 0xbfb8aa3b, v66
	v_rndne_f32_e32 v75, v74
	v_sub_f32_e32 v96, v74, v75
	v_fma_f32 v74, v66, s33, -v74
	v_fmac_f32_e32 v74, 0xb2a5705f, v66
	v_add_f32_e32 v74, v96, v74
	v_exp_f32_e32 v74, v74
	v_cvt_i32_f32_e32 v75, v75
	v_cmp_nlt_f32_e32 vcc, s72, v66
	v_ldexp_f32 v74, v74, v75
	s_nop 0
	v_cndmask_b32_e32 v74, 0, v74, vcc
	v_cmp_ngt_f32_e32 vcc, s79, v66
	s_nop 1
	v_cndmask_b32_e32 v66, v220, v74, vcc
	v_add_f32_e32 v66, 1.0, v66
	v_div_scale_f32 v74, s[12:13], v66, v66, 1.0
	v_rcp_f32_e32 v75, v74
	s_lshl_b64 s[12:13], s[58:59], 11
	v_fma_f32 v96, -v74, v75, 1.0
	v_fmac_f32_e32 v75, v96, v75
	v_div_scale_f32 v96, vcc, 1.0, v66, 1.0
	v_mul_f32_e32 v98, v96, v75
	v_fma_f32 v99, -v74, v98, v96
	v_fmac_f32_e32 v98, v99, v75
	v_fma_f32 v74, -v74, v98, v96
	v_div_fmas_f32 v74, v74, v75, v98
	ds_read2st64_b32 v[98:99], v78 offset1:8
	v_div_fixup_f32 v103, v74, v66, 1.0
	v_lshl_add_u64 v[74:75], v[12:13], 0, s[12:13]
	v_add_co_u32_e32 v100, vcc, s91, v74
	v_add_f32_e32 v66, -1.0, v103
	s_nop 0
	v_addc_co_u32_e32 v101, vcc, 0, v75, vcc
	s_mov_b32 s12, 0x2240000
	s_waitcnt lgkmcnt(0)
	global_store_dword v[74:75], v98, off
	s_waitcnt vmcnt(1)
	v_fma_f32 v66, v66, v76, 1.0
	v_add_co_u32_e32 v98, vcc, s12, v74
	v_mul_f32_e32 v104, v77, v99
	v_mul_f32_e32 v66, v99, v66
	v_addc_co_u32_e32 v99, vcc, 0, v75, vcc
	global_store_dword v[98:99], v66, off
	ds_read_b32 v66, v78 offset:4096
	s_mov_b32 s12, 0x3360000
	v_add_co_u32_e32 v98, vcc, s12, v74
	s_mov_b32 s12, 0x66c0000
	s_nop 0
	v_addc_co_u32_e32 v99, vcc, 0, v75, vcc
	s_waitcnt lgkmcnt(0)
	global_store_dword v[98:99], v66, off
	v_add_co_u32_e32 v98, vcc, s12, v74
	global_store_dword v[100:101], v68, off
	s_nop 0
	v_addc_co_u32_e32 v99, vcc, 0, v75, vcc
	global_store_dword v[98:99], v2, off
	v_mul_f32_e32 v2, v104, v104
	ds_bpermute_b32 v2, v82, v2
	s_waitcnt lgkmcnt(0)
	v_fmac_f32_e32 v2, v104, v104
	ds_bpermute_b32 v66, v83, v2
	s_waitcnt lgkmcnt(0)
	v_add_f32_e32 v2, v2, v66
	ds_bpermute_b32 v66, v84, v2
	s_waitcnt lgkmcnt(0)
	v_add_f32_e32 v2, v2, v66
	ds_bpermute_b32 v66, v85, v2
	s_waitcnt lgkmcnt(0)
	v_add_f32_e32 v2, v2, v66
	ds_bpermute_b32 v66, v86, v2
	s_waitcnt lgkmcnt(0)
	v_add_f32_e32 v2, v2, v66
	ds_bpermute_b32 v66, v87, v2
	s_and_saveexec_b64 s[12:13], s[4:5]
	s_cbranch_execz .LBB0_1063
	s_waitcnt lgkmcnt(0)
	v_add_f32_e32 v2, v2, v66
	v_mov_b32_e32 v66, s61
	ds_write_b32 v66, v2 offset:32768
